# attention unit: pass-1 first key tile and the query's three gate values loaded with the Q loads at the unit top (were load+wait at each use); pass 2 reuses pass 1's first key tile; on top of v94
# speedup vs baseline: 1.0195x; 1.0038x over previous
.LBB0_1182:
	v_mov_b32_e32 v32, v131
	s_nop 1
	v_permlane32_swap_b32_e32 v131, v32
	v_add_f32_e32 v32, v131, v32
	v_div_scale_f32 v34, s[0:1], v32, v32, 1.0
	v_rcp_f32_e32 v35, v34
	v_cmp_lt_f32_e64 s[12:13], 0, v32
	s_lshl_b32 s48, s58, 1
	v_mov_b32_e32 v131, v177
	v_fma_f32 v36, -v34, v35, 1.0
	v_fmac_f32_e32 v35, v36, v35
	v_div_scale_f32 v36, vcc, 1.0, v32, 1.0
	v_mul_f32_e32 v37, v36, v35
	v_fma_f32 v38, -v34, v37, v36
	v_fmac_f32_e32 v37, v38, v35
	v_fma_f32 v34, -v34, v37, v36
	v_div_fmas_f32 v34, v34, v35, v37
	v_div_fixup_f32 v32, v34, v32, 1.0
	ds_read2st64_b32 v[34:35], v157 offset1:8
	ds_read2st64_b32 v[36:37], v157 offset0:128 offset1:136
	v_cndmask_b32_e64 v32, 0, v32, s[12:13]
	v_readlane_b32 s0, v253, 3
	s_add_i32 s41, s41, s0
	s_add_i32 s40, s40, s0
	s_cmpk_gt_i32 s41, 0x3ff
	v_readlane_b32 s1, v253, 4
	s_waitcnt vmcnt(0)
	v_mov_b32_e32 v33, v248
	v_mul_f32_e32 v32, v33, v32
	s_waitcnt lgkmcnt(1)
	v_pk_fma_f32 v[16:17], v[16:17], v[32:33], v[34:35] op_sel_hi:[1,0,1]
	s_waitcnt lgkmcnt(0)
	v_pk_fma_f32 v[0:1], v[0:1], v[32:33], v[36:37] op_sel_hi:[1,0,1]
	ds_read2st64_b32 v[34:35], v157 offset0:16 offset1:24
	ds_read2st64_b32 v[36:37], v157 offset0:144 offset1:152
	v_cvt_pk_bf16_f32 v0, v0, v1
	v_cvt_pk_bf16_f32 v16, v16, v17
	s_waitcnt lgkmcnt(1)
	v_pk_fma_f32 v[18:19], v[18:19], v[32:33], v[34:35] op_sel_hi:[1,0,1]
	s_waitcnt lgkmcnt(0)
	v_pk_fma_f32 v[2:3], v[2:3], v[32:33], v[36:37] op_sel_hi:[1,0,1]
	ds_read2st64_b32 v[34:35], v157 offset0:32 offset1:40
	ds_read2st64_b32 v[36:37], v157 offset0:160 offset1:168
	v_cvt_pk_bf16_f32 v1, v2, v3
	v_cvt_pk_bf16_f32 v17, v18, v19
	s_waitcnt lgkmcnt(1)
	v_pk_fma_f32 v[20:21], v[20:21], v[32:33], v[34:35] op_sel_hi:[1,0,1]
	s_waitcnt lgkmcnt(0)
	v_pk_fma_f32 v[4:5], v[4:5], v[32:33], v[36:37] op_sel_hi:[1,0,1]
	ds_read2st64_b32 v[34:35], v157 offset0:48 offset1:56
	ds_read2st64_b32 v[36:37], v157 offset0:176 offset1:184
	s_waitcnt lgkmcnt(1)
	v_pk_fma_f32 v[22:23], v[22:23], v[32:33], v[34:35] op_sel_hi:[1,0,1]
	s_waitcnt lgkmcnt(0)
	v_pk_fma_f32 v[6:7], v[6:7], v[32:33], v[36:37] op_sel_hi:[1,0,1]
	ds_read2st64_b32 v[34:35], v157 offset0:64 offset1:72
	ds_read2st64_b32 v[36:37], v157 offset0:192 offset1:200
	s_waitcnt lgkmcnt(1)
	v_pk_fma_f32 v[24:25], v[24:25], v[32:33], v[34:35] op_sel_hi:[1,0,1]
	s_waitcnt lgkmcnt(0)
	v_pk_fma_f32 v[8:9], v[8:9], v[32:33], v[36:37] op_sel_hi:[1,0,1]
	ds_read2st64_b32 v[34:35], v157 offset0:80 offset1:88
	ds_read2st64_b32 v[36:37], v157 offset0:208 offset1:216
	s_waitcnt lgkmcnt(1)
	v_pk_fma_f32 v[26:27], v[26:27], v[32:33], v[34:35] op_sel_hi:[1,0,1]
	s_waitcnt lgkmcnt(0)
	v_pk_fma_f32 v[10:11], v[10:11], v[32:33], v[36:37] op_sel_hi:[1,0,1]
	ds_read2st64_b32 v[34:35], v157 offset0:96 offset1:104
	ds_read2st64_b32 v[36:37], v157 offset0:224 offset1:232
	s_waitcnt lgkmcnt(1)
	v_pk_fma_f32 v[28:29], v[28:29], v[32:33], v[34:35] op_sel_hi:[1,0,1]
	s_waitcnt lgkmcnt(0)
	v_pk_fma_f32 v[12:13], v[12:13], v[32:33], v[36:37] op_sel_hi:[1,0,1]
	ds_read2st64_b32 v[34:35], v157 offset0:112 offset1:120
	ds_read2st64_b32 v[36:37], v157 offset0:240 offset1:248
	s_waitcnt lgkmcnt(1)
	v_pk_fma_f32 v[30:31], v[30:31], v[32:33], v[34:35] op_sel_hi:[1,0,1]
	s_waitcnt lgkmcnt(0)
	v_pk_fma_f32 v[14:15], v[14:15], v[32:33], v[36:37] op_sel_hi:[1,0,1]
	v_lshl_add_u64 v[32:33], v[132:133], 1, s[22:23]
	v_lshl_add_u64 v[32:33], v[32:33], 0, s[48:49]
	v_lshl_add_u64 v[32:33], v[32:33], 0, v[130:131]
	global_store_dwordx2 v[32:33], v[0:1], off offset:64
	v_cvt_pk_bf16_f32 v0, v20, v21
	v_cvt_pk_bf16_f32 v1, v22, v23
	global_store_dwordx2 v[32:33], v[0:1], off offset:16
	v_cvt_pk_bf16_f32 v0, v4, v5
	v_cvt_pk_bf16_f32 v1, v6, v7
	global_store_dwordx2 v[32:33], v[0:1], off offset:80
	v_cvt_pk_bf16_f32 v0, v24, v25
	v_cvt_pk_bf16_f32 v1, v26, v27
	global_store_dwordx2 v[32:33], v[0:1], off offset:32
	v_cvt_pk_bf16_f32 v0, v8, v9
	v_cvt_pk_bf16_f32 v1, v10, v11
	global_store_dwordx2 v[32:33], v[0:1], off offset:96
	v_cvt_pk_bf16_f32 v0, v28, v29
	v_cvt_pk_bf16_f32 v1, v30, v31
	global_store_dwordx2 v[32:33], v[0:1], off offset:48
	v_cvt_pk_bf16_f32 v0, v12, v13
	v_cvt_pk_bf16_f32 v1, v14, v15
	global_store_dwordx2 v[32:33], v[16:17], off
	global_store_dwordx2 v[32:33], v[0:1], off offset:112
	s_barrier
	s_cbranch_scc1 .LBB0_1316
.LBB0_1183:
	s_bfe_u32 s0, s41, 0x50003
	s_ashr_i32 s86, s41, 3
	s_and_b32 s36, s86, 0xffffffe0
	s_and_b32 s1, s41, 0x100
	s_xor_b32 s12, s0, 31
	s_cmp_eq_u32 s1, 0
	s_cselect_b32 s67, s0, s12
	s_lshl_b32 s0, s41, 2
	s_and_b32 s0, s0, 12
	s_or_b32 s33, s67, s36
	s_or_b32 s17, s0, s66
	s_lshl_b32 s0, s41, 11
	v_lshl_add_u32 v1, s33, 6, v158
	s_and_b32 s0, s0, 0x2000
	v_add_u32_e32 v36, s0, v1
	v_ashrrev_i32_e32 v37, 31, v36
	v_lshlrev_b64 v[2:3], 11, v[36:37]
	v_lshl_add_u64 v[2:3], s[18:19], 0, v[2:3]
	s_lshl_b32 s48, s17, 7
	v_lshl_add_u64 v[2:3], v[2:3], 0, s[48:49]
	v_lshl_add_u64 v[2:3], v[2:3], 0, v[176:177]
	global_load_dwordx4 v[100:103], v[2:3], off
	global_load_dwordx4 v[104:107], v[2:3], off offset:32
	global_load_dwordx4 v[108:111], v[2:3], off offset:64
	global_load_dwordx4 v[112:115], v[2:3], off offset:96
	s_and_b32 s100, s41, 7
	s_lshl_b32 s100, s100, 16
	v_readlane_b32 s98, v255, 10
	v_readlane_b32 s99, v255, 11
	s_nop 1
	s_add_u32 s98, s98, s100
	s_addc_u32 s99, s99, 0
	v_lshl_add_u64 v[242:243], v[120:121], 1, s[98:99]
	global_load_dwordx4 v[238:241], v[242:243], off
	v_mov_b64_e32 v[246:247], s[20:21]
	s_movk_i32 s100, 0xc0
	v_mad_i64_i32 v[246:247], s[98:99], v36, s100, v[246:247]
	s_lshl_b32 s100, s17, 2
	s_mov_b32 s101, 0
	v_lshl_add_u64 v[246:247], v[246:247], 0, s[100:101]
	global_load_dword v244, v[246:247], off
	global_load_dword v245, v[246:247], off offset:64
	global_load_dword v248, v[246:247], off offset:128
	s_waitcnt vmcnt(7)
	v_and_b32_e32 v0, 0xffff0000, v100
	v_lshlrev_b32_e32 v2, 16, v100
	v_mul_f32_e32 v0, v0, v0
	v_fmac_f32_e32 v0, v2, v2
	v_lshlrev_b32_e32 v2, 16, v101
	v_fmac_f32_e32 v0, v2, v2
	v_and_b32_e32 v2, 0xffff0000, v101
	v_fmac_f32_e32 v0, v2, v2
	v_lshlrev_b32_e32 v2, 16, v102
	v_fmac_f32_e32 v0, v2, v2
	v_and_b32_e32 v2, 0xffff0000, v102
	v_fmac_f32_e32 v0, v2, v2
	v_lshlrev_b32_e32 v2, 16, v103
	v_fmac_f32_e32 v0, v2, v2
	v_and_b32_e32 v2, 0xffff0000, v103
	v_fmac_f32_e32 v0, v2, v2
	s_waitcnt vmcnt(6)
	v_lshlrev_b32_e32 v2, 16, v104
	v_fmac_f32_e32 v0, v2, v2
	v_and_b32_e32 v2, 0xffff0000, v104
	v_fmac_f32_e32 v0, v2, v2
	v_lshlrev_b32_e32 v2, 16, v105
	v_fmac_f32_e32 v0, v2, v2
	v_and_b32_e32 v2, 0xffff0000, v105
	v_fmac_f32_e32 v0, v2, v2
	v_lshlrev_b32_e32 v2, 16, v106
	v_fmac_f32_e32 v0, v2, v2
	v_and_b32_e32 v2, 0xffff0000, v106
	v_fmac_f32_e32 v0, v2, v2
	v_lshlrev_b32_e32 v2, 16, v107
	v_fmac_f32_e32 v0, v2, v2
	v_and_b32_e32 v2, 0xffff0000, v107
	v_fmac_f32_e32 v0, v2, v2
	s_waitcnt vmcnt(5)
	v_lshlrev_b32_e32 v2, 16, v108
	v_fmac_f32_e32 v0, v2, v2
	v_and_b32_e32 v2, 0xffff0000, v108
	v_fmac_f32_e32 v0, v2, v2
	v_lshlrev_b32_e32 v2, 16, v109
	v_fmac_f32_e32 v0, v2, v2
	v_and_b32_e32 v2, 0xffff0000, v109
	v_fmac_f32_e32 v0, v2, v2
	v_lshlrev_b32_e32 v2, 16, v110
	v_fmac_f32_e32 v0, v2, v2
	v_and_b32_e32 v2, 0xffff0000, v110
	v_fmac_f32_e32 v0, v2, v2
	v_lshlrev_b32_e32 v2, 16, v111
	v_fmac_f32_e32 v0, v2, v2
	v_and_b32_e32 v2, 0xffff0000, v111
	v_fmac_f32_e32 v0, v2, v2
	s_waitcnt vmcnt(4)
	v_lshlrev_b32_e32 v2, 16, v112
	v_fmac_f32_e32 v0, v2, v2
	v_and_b32_e32 v2, 0xffff0000, v112
	v_fmac_f32_e32 v0, v2, v2
	v_lshlrev_b32_e32 v2, 16, v113
	v_fmac_f32_e32 v0, v2, v2
	v_and_b32_e32 v2, 0xffff0000, v113
	v_fmac_f32_e32 v0, v2, v2
	v_lshlrev_b32_e32 v2, 16, v114
	v_fmac_f32_e32 v0, v2, v2
	v_and_b32_e32 v2, 0xffff0000, v114
	v_fmac_f32_e32 v0, v2, v2
	v_lshlrev_b32_e32 v2, 16, v115
	v_fmac_f32_e32 v0, v2, v2
	v_and_b32_e32 v2, 0xffff0000, v115
	v_fmac_f32_e32 v0, v2, v2
	v_mov_b32_e32 v2, v0
	s_nop 1
	v_permlane32_swap_b32_e32 v0, v2
	s_mov_b64 s[0:1], exec
	v_readlane_b32 s12, v255, 16
	v_readlane_b32 s13, v255, 17
	s_and_b64 s[12:13], s[0:1], s[12:13]
	s_mov_b64 exec, s[12:13]
	s_cbranch_execz .LBB0_1186
	s_mov_b64 s[12:13], 0
	v_mov_b32_e32 v3, v201
	v_mov_b32_e32 v4, v200

.LBB0_1186:
	s_or_b64 exec, exec, s[0:1]
	v_lshlrev_b64 v[132:133], 10, v[36:37]
	s_lshl_b32 s58, s17, 6
	s_and_saveexec_b64 s[0:1], s[4:5]
	ds_write_b32 v159, v177
	s_or_b64 exec, exec, s[0:1]
	s_and_saveexec_b64 s[0:1], s[6:7]
	ds_write_b32 v160, v177
	s_or_b64 exec, exec, s[0:1]
	s_lshl_b32 s0, s33, 2
	s_and_b32 s88, s41, 7
	s_addk_i32 s0, 0x42
	s_ashr_i32 s16, s0, 6
	s_lshl_b32 s0, s88, 16
	v_readlane_b32 s1, v255, 10
	s_add_u32 s0, s1, s0
	v_readlane_b32 s1, v255, 11
	s_addc_u32 s1, s1, 0
	s_waitcnt lgkmcnt(0)
	v_lshl_add_u64 v[38:39], v[120:121], 1, s[0:1]
	s_barrier
	s_cmp_gt_i32 s16, 1
	s_cselect_b64 s[14:15], -1, 0
	s_cmp_lt_i32 s16, 2
	s_waitcnt vmcnt(0)
	ds_write_b128 v163, v[238:241]
	s_cbranch_scc1 .LBB0_1192
	v_add_co_u32_e32 v4, vcc, 0x2000, v38
	s_nop 1
	v_addc_co_u32_e32 v5, vcc, 0, v39, vcc
	global_load_dwordx4 v[32:35], v[4:5], off

.LBB0_1199:
	s_lshl_b32 s0, s88, 15
	s_lshl_b32 s0, s0, 1
	v_readlane_b32 s1, v255, 12
	v_mov_b64_e32 v[0:1], s[20:21]
	s_movk_i32 s31, 0xc0
	s_add_u32 s0, s1, s0
	v_readlane_b32 s1, v255, 14
	v_mad_i64_i32 v[0:1], s[34:35], v36, s31, v[0:1]
	s_addc_u32 s1, s1, 0
	s_lshl_b32 s34, s17, 2
	s_mov_b32 s35, s49
	v_lshl_add_u64 v[136:137], v[0:1], 0, s[34:35]
	v_readlane_b32 s34, v253, 29
	v_mov_b32_e32 v0, v37
	v_readlane_b32 s35, v253, 30
	s_nop 0
	v_permlane32_swap_b32_e32 v37, v0
	s_and_b64 vcc, exec, s[34:35]
	v_lshlrev_b32_e32 v72, 1, v122
	s_cbranch_vccz .LBB0_1201
	v_mov_b32_e32 v73, v177
	v_lshl_add_u64 v[2:3], s[0:1], 0, v[72:73]
	v_lshl_add_u64 v[2:3], v[124:125], 1, v[2:3]
	global_load_dwordx4 v[96:99], v[2:3], off
.LBB0_1201:
	s_andn2_b64 vcc, exec, s[14:15]
	s_waitcnt vmcnt(0)
	v_mov_b32_e32 v74, v244
	ds_write_b128 v163, v[238:241]
	ds_write_b16 v167, v96 offset:9216
	ds_write_b16_d16_hi v167, v96 offset:9352
	ds_write_b16 v167, v97 offset:9488
	ds_write_b16_d16_hi v167, v97 offset:9624
	ds_write_b16 v167, v98 offset:9760
	ds_write_b16_d16_hi v167, v98 offset:9896
	ds_write_b16 v167, v99 offset:10032
	ds_write_b16_d16_hi v167, v99 offset:10168
	s_cbranch_vccnz .LBB0_1203
	v_mov_b32_e32 v73, v177
	v_lshl_add_u64 v[2:3], s[0:1], 0, v[72:73]
	v_add_co_u32_e32 v4, vcc, 0x2000, v38
	v_lshl_add_u64 v[2:3], v[124:125], 1, v[2:3]
	s_nop 0
	v_addc_co_u32_e32 v5, vcc, 0, v39, vcc
	v_add_co_u32_e32 v2, vcc, 0x2000, v2
	s_nop 1
	v_addc_co_u32_e32 v3, vcc, 0, v3, vcc
	global_load_dwordx4 v[64:67], v[4:5], off
	global_load_dwordx4 v[96:99], v[2:3], off

.LBB0_1298:
	v_mov_b32_e32 v32, v73
	s_nop 1
	v_permlane32_swap_b32_e32 v73, v32
	v_add_f32_e32 v32, v73, v32
	v_div_scale_f32 v34, s[16:17], v32, v32, 1.0
	v_rcp_f32_e32 v35, v34
	v_cmp_lt_f32_e64 s[14:15], 0, v32
	s_lshl_b32 s0, s88, 19
	v_readlane_b32 s2, v255, 7
	v_fma_f32 v36, -v34, v35, 1.0
	v_fmac_f32_e32 v35, v36, v35
	v_div_scale_f32 v36, vcc, 1.0, v32, 1.0
	v_mul_f32_e32 v37, v36, v35
	v_fma_f32 v38, -v34, v37, v36
	v_fmac_f32_e32 v37, v38, v35
	v_fma_f32 v34, -v34, v37, v36
	v_div_fmas_f32 v34, v34, v35, v37
	v_div_fixup_f32 v32, v34, v32, 1.0
	ds_read2st64_b32 v[34:35], v157 offset0:128 offset1:136
	v_cndmask_b32_e64 v32, 0, v32, s[14:15]
	s_lshl_b32 s14, s0, 1
	s_add_u32 s0, s30, s14
	s_addc_u32 s1, s3, 0
	s_add_u32 s16, s2, s14
	v_readlane_b32 s2, v255, 9
	s_addc_u32 s17, s2, 0
	s_add_i32 s14, s33, -8
	s_cmp_gt_i32 s33, 7
	s_cselect_b32 s14, s14, 0
	s_ashr_i32 s15, s14, 31
	s_lshl_b64 s[34:35], s[14:15], 13
	s_add_u32 s34, s0, s34
	s_addc_u32 s35, s1, s35
	s_and_b64 vcc, exec, s[12:13]
	s_waitcnt vmcnt(0)
	v_mov_b32_e32 v33, v245
	v_mul_f32_e32 v36, v33, v32
	s_waitcnt lgkmcnt(0)
	v_fma_f32 v0, v0, v36, v34
	v_fmac_f32_e32 v35, v1, v36
	ds_write2st64_b32 v157, v0, v35 offset0:128 offset1:136
	ds_read2st64_b32 v[0:1], v157 offset0:16 offset1:24
	ds_read2st64_b32 v[32:33], v157 offset1:8
	s_waitcnt lgkmcnt(1)
	v_fma_f32 v0, v18, v36, v0
	v_fmac_f32_e32 v1, v19, v36
	ds_write2st64_b32 v157, v0, v1 offset0:16 offset1:24
	ds_read2st64_b32 v[0:1], v157 offset0:32 offset1:40
	s_waitcnt lgkmcnt(2)
	v_fma_f32 v16, v16, v36, v32
	v_fmac_f32_e32 v33, v17, v36
	ds_write2st64_b32 v157, v16, v33 offset1:8
	ds_read2st64_b32 v[16:17], v157 offset0:144 offset1:152
	s_waitcnt lgkmcnt(2)
	v_fma_f32 v0, v20, v36, v0
	v_fmac_f32_e32 v1, v21, v36
	ds_write2st64_b32 v157, v0, v1 offset0:32 offset1:40
	ds_read2st64_b32 v[0:1], v157 offset0:48 offset1:56
	s_waitcnt lgkmcnt(2)
	v_fma_f32 v2, v2, v36, v16
	v_fmac_f32_e32 v17, v3, v36
	ds_write2st64_b32 v157, v2, v17 offset0:144 offset1:152
	ds_read2st64_b32 v[2:3], v157 offset0:160 offset1:168
	s_waitcnt lgkmcnt(2)
	v_fma_f32 v0, v22, v36, v0
	v_fmac_f32_e32 v1, v23, v36
	ds_write2st64_b32 v157, v0, v1 offset0:48 offset1:56
	ds_read2st64_b32 v[0:1], v157 offset0:64 offset1:72
	s_waitcnt lgkmcnt(2)
	v_fma_f32 v2, v4, v36, v2
	v_fmac_f32_e32 v3, v5, v36
	ds_write2st64_b32 v157, v2, v3 offset0:160 offset1:168
	ds_read2st64_b32 v[2:3], v157 offset0:176 offset1:184
	s_waitcnt lgkmcnt(2)
	v_fma_f32 v0, v24, v36, v0
	v_fmac_f32_e32 v1, v25, v36
	ds_write2st64_b32 v157, v0, v1 offset0:64 offset1:72
	ds_read2st64_b32 v[0:1], v157 offset0:80 offset1:88
	s_waitcnt lgkmcnt(2)
	v_fma_f32 v2, v6, v36, v2
	v_fmac_f32_e32 v3, v7, v36
	ds_write2st64_b32 v157, v2, v3 offset0:176 offset1:184
	ds_read2st64_b32 v[2:3], v157 offset0:192 offset1:200
	s_waitcnt lgkmcnt(2)
	v_fma_f32 v0, v26, v36, v0
	v_fmac_f32_e32 v1, v27, v36
	ds_write2st64_b32 v157, v0, v1 offset0:80 offset1:88
	ds_read2st64_b32 v[0:1], v157 offset0:96 offset1:104
	s_waitcnt lgkmcnt(2)
	v_fma_f32 v2, v8, v36, v2
	v_fmac_f32_e32 v3, v9, v36
	ds_write2st64_b32 v157, v2, v3 offset0:192 offset1:200
	ds_read2st64_b32 v[2:3], v157 offset0:208 offset1:216
	s_waitcnt lgkmcnt(2)
	v_fma_f32 v0, v28, v36, v0
	v_fmac_f32_e32 v1, v29, v36
	ds_write2st64_b32 v157, v0, v1 offset0:96 offset1:104
	ds_read2st64_b32 v[0:1], v157 offset0:112 offset1:120
	s_waitcnt lgkmcnt(2)
	v_fma_f32 v2, v10, v36, v2
	v_fmac_f32_e32 v3, v11, v36
	ds_write2st64_b32 v157, v2, v3 offset0:208 offset1:216
	ds_read2st64_b32 v[2:3], v157 offset0:224 offset1:232
	s_waitcnt lgkmcnt(2)
	v_fma_f32 v0, v30, v36, v0
	v_fmac_f32_e32 v1, v31, v36
	ds_write2st64_b32 v157, v0, v1 offset0:112 offset1:120
	v_lshl_add_u64 v[0:1], v[120:121], 1, s[34:35]
	global_load_dwordx4 v[116:119], v[0:1], off
	s_waitcnt lgkmcnt(1)
	v_fma_f32 v2, v12, v36, v2
	v_fmac_f32_e32 v3, v13, v36
	ds_write2st64_b32 v157, v2, v3 offset0:224 offset1:232
	ds_read2st64_b32 v[2:3], v157 offset0:240 offset1:248
	s_waitcnt lgkmcnt(0)
	v_fma_f32 v2, v14, v36, v2
	v_fmac_f32_e32 v3, v15, v36
	ds_write2st64_b32 v157, v2, v3 offset0:240 offset1:248
	s_cbranch_vccnz .LBB0_1300
	s_lshl_b64 s[34:35], s[14:15], 12
	s_lshl_b64 s[34:35], s[34:35], 1
	s_add_u32 s34, s16, s34
	s_addc_u32 s35, s17, s35
	v_mov_b32_e32 v73, v177
	v_lshl_add_u64 v[0:1], s[34:35], 0, v[72:73]
	v_lshl_add_u64 v[0:1], v[124:125], 1, v[0:1]
	global_load_dwordx4 v[96:99], v[0:1], off
